# attention: per-XCD work queues (K/V of a (b,h) stay in one L2) + per-lane DMA offset table instead of per-tile address recomputation; mLSTM pass 2 placed statically
# speedup vs baseline: 1.0289x; 1.0069x over previous
; __device__ __forceinline__ unsigned char* WS(const Params& p) { unsigned z = 0; asm volatile("" : "+s"(z)); return p.ws + z; }
; __device__ __forceinline__ int opaque_tid() { int t = threadIdx.x; asm volatile("" : "+v"(t)); return t; }
; __device__ __forceinline__ void run_phase(const Params& p, int ph, char* lds, int mode) {
;     ...
;       unsigned* ctr = (unsigned*)(WS(p) + OFF_CTRL) + (mode ? 8 + mode : l);
;       int* sh = (int*)(lds + 74240);
;       for (;;) {
;         __syncthreads();
;         if (opaque_tid() == 0) *sh = (int)atomicAdd(ctr, 1u);
;         __syncthreads();
;         int it = *sh;
;         if (mode == 1) { if (it >= 192) break; }
;         else if (mode == 2) { if (it >= 512) break; it += 208; }
;         const int ntot = 192 + 16 + 512 + 1024 + N_CONV_FFN + (l == 0 ? N_CONV_MIX : 0);
;         if (it >= ntot) break;
;         unsigned* flags = (unsigned*)(WS(p) + OFF_CTRL) + 16 + l * 16;
;         if (it < 192) { if (EN(20)) rwkv_scan2_item(p, it, lds); }
;         else if (it < 208) { if (EN(21)) ml_p2_item(p, it - 192, flags + (it - 192), lds); }
;         else if (it < 720) { const int a = it - 208; if (EN(22)) attn_item(p, l, a & 15, 31 - (a >> 4), lds); }
.LBB0_152:
	s_andn2_b64 vcc, exec, s[24:25]
	s_cbranch_vccnz .LBB0_705
	v_readlane_b32 s2, v255, 13
	s_cmp_lt_i32 s2, 1
	s_mov_b64 s[24:25], -1
	s_cbranch_scc1 .LBB0_642
	v_readlane_b32 s2, v255, 13
	s_cmp_gt_i32 s2, 1
	s_cbranch_scc0 .LBB0_522
	s_mov_b32 s2, s89
	s_add_u32 s24, s46, s2
	s_addc_u32 s25, s47, 0
	s_ashr_i32 s65, s64, 31
	s_lshl_b64 s[2:3], s[64:65], 2
	s_add_u32 s34, s24, s2
	s_addc_u32 s35, s25, s3
	v_readlane_b32 s2, v255, 11
	v_readlane_b32 s3, v255, 12
	s_and_b64 s[2:3], s[2:3], exec
	s_movk_i32 s2, 0x12c0
	s_mov_b32 s6, s64
	s_cselect_b32 s64, s2, 0xf10
	s_lshl_b32 s4, s6, 2
	v_writelane_b32 v255, s4, 18
	s_mov_b32 s4, s6
	v_writelane_b32 v255, s4, 16
	s_lshl_b32 s2, s6, 4
	s_mul_hi_i32 s30, s6, 0xb00000
	s_mul_i32 s31, s6, 0xb00000
	s_lshl_b32 s24, s6, 10
	s_lshl_b32 s26, s6, 8
	v_writelane_b32 v255, s5, 17
	s_lshl_b32 s28, s6, 9
	v_readlane_b32 s4, v252, 35
	s_ashr_i32 s3, s2, 31
	s_ashr_i32 s25, s24, 31
	s_ashr_i32 s27, s26, 31
	s_ashr_i32 s29, s28, 31
	v_readlane_b32 s6, v252, 37
	v_readlane_b32 s14, v252, 45
	v_readlane_b32 s7, v252, 38
	v_readlane_b32 s15, v252, 46
	s_add_u32 s6, s14, s31
	v_readlane_b32 s10, v252, 41
	s_addc_u32 s7, s15, s30
	v_readlane_b32 s11, v252, 42
	s_add_u32 s10, s10, s31
	v_readlane_b32 s12, v252, 43
	v_writelane_b32 v255, s6, 14
	s_addc_u32 s11, s11, s30
	v_readlane_b32 s13, v252, 44
	v_writelane_b32 v255, s7, 15
	s_add_u32 s6, s12, s31
	v_readlane_b32 s8, v252, 39
	v_writelane_b32 v255, s6, 24
	s_addc_u32 s6, s13, s30
	s_lshl_b64 s[24:25], s[24:25], 2
	v_readlane_b32 s9, v252, 40
	v_writelane_b32 v255, s6, 25
	s_add_u32 s8, s8, s24
	v_readlane_b32 s6, v254, 27
	s_addc_u32 s9, s9, s25
	v_readlane_b32 s7, v254, 28
	v_writelane_b32 v255, s11, 26
	s_and_b64 s[30:31], s[6:7], exec
	v_writelane_b32 v255, s10, 27
	v_readlane_b32 s16, v252, 47
	v_readlane_b32 s17, v252, 48
	v_readlane_b32 s18, v252, 49
	v_readlane_b32 s19, v252, 50
	s_cselect_b32 s7, s11, s9
	v_writelane_b32 v255, s8, 28
	s_cselect_b32 s6, s10, s8
	v_readlane_b32 s5, v252, 36
	v_writelane_b32 v255, s9, 29
	v_readlane_b32 s8, v252, 19
	v_readlane_b32 s16, v252, 27
	v_readlane_b32 s17, v252, 28
	s_add_u32 s44, s16, s24
	v_readlane_b32 s18, v252, 29
	v_readlane_b32 s22, v252, 33
	s_addc_u32 s45, s17, s25
	s_lshl_b64 s[24:25], s[26:27], 2
	v_readlane_b32 s19, v252, 30
	v_readlane_b32 s23, v252, 34
	s_add_u32 s22, s18, s24
	v_writelane_b32 v255, s6, 30
	s_addc_u32 s23, s19, s25
	s_add_u32 s4, s4, s24
	v_writelane_b32 v255, s7, 31
	v_readlane_b32 s9, v252, 20
	v_readlane_b32 s10, v252, 21
	v_readlane_b32 s11, v252, 22
	v_readlane_b32 s12, v252, 23
	v_readlane_b32 s13, v252, 24
	v_readlane_b32 s14, v252, 25
	v_readlane_b32 s15, v252, 26
	v_writelane_b32 v255, s4, 20
	s_addc_u32 s4, s5, s25
	v_writelane_b32 v255, s4, 22
	v_readlane_b32 s4, v252, 3
	s_lshl_b64 s[24:25], s[28:29], 2
	v_readlane_b32 s9, v252, 8
	v_readlane_b32 s5, v252, 4
	v_readlane_b32 s10, v252, 9
	s_add_u32 s9, s4, s24
	v_readlane_b32 s11, v252, 10
	s_addc_u32 s10, s5, s25
	s_lshl_b64 s[2:3], s[2:3], 2
	v_readlane_b32 s20, v252, 31
	v_readlane_b32 s21, v252, 32
	s_add_u32 s11, s46, s2
	s_mov_b64 s[20:21], s[34:35]
	s_addc_u32 s65, s47, s3
	v_readlane_b32 s6, v252, 5
	v_readlane_b32 s7, v252, 6
	v_readlane_b32 s8, v252, 7
	v_readlane_b32 s12, v252, 11
	v_readlane_b32 s13, v252, 12
	v_readlane_b32 s14, v252, 13
	v_readlane_b32 s15, v252, 14
	v_readlane_b32 s16, v252, 15
	v_readlane_b32 s17, v252, 16
	v_readlane_b32 s18, v252, 17
	v_readlane_b32 s19, v252, 18
	s_waitcnt lgkmcnt(0)
	s_mov_b32 s2, 0
	s_cmpk_lg_u32 s77, 0x200
	s_cbranch_scc1 .Lplace_off
	s_movk_i32 s2, 0x2d0
.Lplace_off:
	s_nop 0
	v_writelane_b32 v255, s2, 45
	s_cmp_eq_u32 s2, 0
	s_cselect_b32 s3, 0, 1
	s_nop 0
	v_writelane_b32 v255, s3, 52
	s_cbranch_scc1 .LBB0_159
	v_readlane_b32 s78, v252, 0
	s_nop 0
	s_sub_u32 s2, s20, s46
	s_lshl_b32 s2, s2, 7
	s_and_b32 s3, s78, 7
	s_lshl_b32 s3, s3, 6
	s_add_u32 s2, s2, s3
	s_add_u32 s2, s2, 0x400
	s_add_u32 s2, s46, s2
	s_addc_u32 s3, s47, 0
	s_nop 0
	v_writelane_b32 v255, s2, 50
	v_writelane_b32 v255, s3, 51
	s_and_b32 s2, s78, 7
	s_lshl_b32 s2, s2, 1
	s_add_u32 s2, s2, 0xd0
	s_nop 0
	v_writelane_b32 v255, s2, 53
	s_and_b32 s2, s78, 0xff
	s_cmpk_ge_u32 s2, 96
	s_cbranch_scc1 .Lplace_q
	s_lshl_b32 s2, s2, 1
	s_lshr_b32 s78, s78, 8
	s_add_u32 s78, s78, s2
	s_branch .Lsc_entry
.Lplace_q:
	s_cmpk_ge_u32 s2, 104
	s_cbranch_scc1 .LBB0_159
	s_and_b32 s2, s78, 7
	s_lshr_b32 s3, s78, 8
	s_lshl_b32 s3, s3, 3
	s_add_u32 s78, s2, s3
	s_add_u32 s78, s78, 0xc0
	v_mov_b32_e32 v0, s78
	s_mov_b64 s[24:25], -1
	s_movk_i32 s8, 0x8c8
	s_branch .Lq_dispatch

; __device__ __forceinline__ int opaque_tid() { int t = threadIdx.x; asm volatile("" : "+v"(t)); return t; }
; __device__ __forceinline__ void run_phase(const Params& p, int ph, char* lds, int mode) {
;     ...
;       for (;;) {
;         __syncthreads();
;         if (opaque_tid() == 0) *sh = (int)atomicAdd(ctr, 1u);
;         __syncthreads();
.LBB0_159:
	s_waitcnt vmcnt(4)
	v_mov_b32_e32 v0, v198
	s_waitcnt lgkmcnt(0)
	s_barrier
	s_nop 0
	v_cmp_eq_u32_e32 vcc, 0, v0
	s_and_saveexec_b64 s[24:25], vcc
	s_cbranch_execz .LBB0_163
	s_mov_b64 s[28:29], exec
	v_mbcnt_lo_u32_b32 v0, s28, 0
	v_mbcnt_hi_u32_b32 v0, s29, v0
	v_cmp_eq_u32_e32 vcc, 0, v0
	s_and_saveexec_b64 s[26:27], vcc
	s_cbranch_execz .LBB0_162
	s_bcnt1_i32_b64 s2, s[28:29]
	v_mov_b32_e32 v1, s2
	v_readlane_b32 s2, v255, 52
	s_nop 0
	s_cmp_eq_u32 s2, 0
	s_cbranch_scc1 .Lq_glob
	v_readlane_b32 vcc_lo, v255, 50
	v_readlane_b32 vcc_hi, v255, 51
	s_nop 4
	global_atomic_add v1, v3, v1, vcc sc0
	s_branch .LBB0_162
.Lq_glob:
	global_atomic_add v1, v3, v1, s[20:21] sc0

; __device__ __forceinline__ unsigned char* WS(const Params& p) { unsigned z = 0; asm volatile("" : "+s"(z)); return p.ws + z; }
; __device__ __forceinline__ int opaque_tid() { int t = threadIdx.x; asm volatile("" : "+v"(t)); return t; }
; __device__ __forceinline__ void run_phase(const Params& p, int ph, char* lds, int mode) {
;     ...
;         if (opaque_tid() == 0) *sh = (int)atomicAdd(ctr, 1u);
;         __syncthreads();
;         int it = *sh;
;         if (mode == 1) { if (it >= 192) break; }
;         else if (mode == 2) { if (it >= 512) break; it += 208; }
;         const int ntot = 192 + 16 + 512 + 1024 + N_CONV_FFN + (l == 0 ? N_CONV_MIX : 0);
;         if (it >= ntot) break;
;         unsigned* flags = (unsigned*)(WS(p) + OFF_CTRL) + 16 + l * 16;
;         if (it < 192) { if (EN(20)) rwkv_scan2_item(p, it, lds); }
;         else if (it < 208) { if (EN(21)) ml_p2_item(p, it - 192, flags + (it - 192), lds); }
;         else if (it < 720) { const int a = it - 208; if (EN(22)) attn_item(p, l, a & 15, 31 - (a >> 4), lds); }
.LBB0_163:
	s_movk_i32 s8, 0x8c8
	s_or_b64 exec, exec, s[24:25]
	v_readlane_b32 s2, v255, 2
	s_waitcnt lgkmcnt(0)
	s_barrier
	v_mov_b32_e32 v0, s2
	ds_read_b32 v0, v0
	s_mov_b64 s[24:25], -1
	v_readlane_b32 s2, v255, 52
	s_waitcnt lgkmcnt(0)
	s_cmp_eq_u32 s2, 0
	s_cbranch_scc1 .Lq_global_it
	v_readfirstlane_b32 s78, v0
	s_nop 0
	s_cmpk_lt_u32 s78, 64
	s_cbranch_scc1 .Lq_attn_item
	s_mov_b32 s2, 0
	s_nop 0
	v_writelane_b32 v255, s2, 52
	s_branch .LBB0_159
.Lq_attn_item:
	s_lshr_b32 s2, s78, 1
	s_lshl_b32 s2, s2, 4
	s_and_b32 s78, s78, 1
	s_add_u32 s78, s78, s2
	v_readlane_b32 s2, v255, 53
	s_nop 0
	s_add_u32 s78, s78, s2
	v_mov_b32_e32 v0, s78
	s_branch .Lq_dispatch
.Lq_global_it:
	v_readlane_b32 vcc_lo, v255, 45
	s_nop 1
	v_add_u32_e32 v0, vcc_lo, v0
	v_cmp_le_i32_e32 vcc, s64, v0
	v_readfirstlane_b32 s78, v0
	s_cbranch_vccnz .LBB0_158
.Lq_dispatch:
	s_mov_b32 s2, s89
	s_cmpk_gt_i32 s78, 0xbf
	s_cbranch_scc0 .LBB0_478
	s_add_u32 s24, s11, s2
	s_addc_u32 s25, s65, 0
	s_cmpk_gt_u32 s78, 0xcf
	s_mov_b64 s[26:27], -1
	s_cbranch_scc0 .LBB0_452
	s_cmpk_gt_u32 s78, 0x2cf
	s_cbranch_scc0 .LBB0_382
	s_cmpk_gt_u32 s78, 0x6cf
	s_cbranch_scc0 .LBB0_328
	s_cmpk_gt_u32 s78, 0xf0f
	s_cbranch_scc0 .LBB0_285
	s_add_i32 s30, s78, 0xfffff0f0
	s_mov_b32 s2, s89
	s_add_u32 s28, s46, s2
	s_addc_u32 s29, s47, 0
	s_cmpk_gt_u32 s30, 0x23f
	s_cbranch_scc0 .LBB0_248
	s_cmpk_gt_u32 s30, 0x26f
	s_cbranch_scc0 .LBB0_211
	s_cmpk_gt_u32 s30, 0x2af
	s_cbranch_scc0 .LBB0_175
; __device__ __forceinline__ void conv_tile(const float* __restrict__ s0, const float* __restrict__ s1, int mode, int K, int Nsrc,
;                           const float* __restrict__ gain, bf16_t* __restrict__ dst, int kt, int nt, char* ldsraw) {
;     ...
;   for (int i = 0; i < 16; i++) {
;     const int idx = tid + 256 * i; const int kk = idx >> 6, nn = idx & 63; const int n = nt * 64 + nn, k = kt * 64 + kk;
;     const float* sp; int col;
;     if (mode == 0) { sp = s0; col = (n < Nsrc) ? n : (Nsrc - 1); }
;     else { const int g = n >> 5, r = n & 31; col = g * 16 + (r & 15); sp = (r < 16) ? s0 : s1; }
;     vals[i] = __builtin_nontemporal_load(sp + (size_t)k * Nsrc + col);
;     gv[i] = gp[k];
;   }
; #pragma unroll
;   for (int i = 0; i < 16; i++) {
;     const int idx = tid + 256 * i; const int kk = idx >> 6, nn = idx & 63; const int n = nt * 64 + nn;
;     float v = gain ? vals[i] * gv[i] : vals[i];
;     if (mode == 0 && n >= Nsrc) v = 0.f;
;     lds[kk * 65 + nn] = v;
;   }
;   __syncthreads();
	s_lshl_b32 s3, s30, 2
	v_mov_b32_e32 v4, v198
	s_and_b32 s3, s3, 0x7fffffc0
	s_add_i32 s88, s3, 0xfffff540
	v_ashrrev_i32_e32 v5, 6, v4
	s_lshl_b32 s2, s30, 6
	v_add_u32_e32 v0, s88, v5
	v_and_b32_e32 v8, 63, v4
	s_and_b32 s2, s2, 0x3c0
	v_ashrrev_i32_e32 v1, 31, v0
	v_readlane_b32 s4, v254, 9
	v_or_b32_e32 v2, s2, v8
	v_lshlrev_b64 v[0:1], 12, v[0:1]
	v_readlane_b32 s5, v254, 10
	v_lshlrev_b32_e32 v2, 2, v2
	s_mov_b32 s3, 0
	v_lshl_add_u64 v[0:1], s[4:5], 0, v[0:1]
	v_lshl_add_u64 v[0:1], v[0:1], 0, v[2:3]
	global_load_dword v9, v[0:1], off nt
	v_add_u32_e32 v0, 0x100, v4
	v_ashrrev_i32_e32 v10, 6, v0
	v_add_u32_e32 v0, s88, v10
	v_ashrrev_i32_e32 v1, 31, v0
	v_lshlrev_b64 v[0:1], 12, v[0:1]
	v_lshl_add_u64 v[0:1], s[4:5], 0, v[0:1]
	v_lshl_add_u64 v[0:1], v[0:1], 0, v[2:3]
	global_load_dword v11, v[0:1], off nt
	v_add_u32_e32 v0, 0x200, v4
	v_ashrrev_i32_e32 v12, 6, v0
	v_add_u32_e32 v0, s88, v12
	v_ashrrev_i32_e32 v1, 31, v0
	v_lshlrev_b64 v[0:1], 12, v[0:1]
	v_lshl_add_u64 v[0:1], s[4:5], 0, v[0:1]
	v_lshl_add_u64 v[0:1], v[0:1], 0, v[2:3]
	global_load_dword v13, v[0:1], off nt
	v_add_u32_e32 v0, 0x300, v4
	v_ashrrev_i32_e32 v14, 6, v0
	v_add_u32_e32 v0, s88, v14
	v_ashrrev_i32_e32 v1, 31, v0
	v_lshlrev_b64 v[0:1], 12, v[0:1]
	v_lshl_add_u64 v[0:1], s[4:5], 0, v[0:1]
	v_lshl_add_u64 v[0:1], v[0:1], 0, v[2:3]
	global_load_dword v15, v[0:1], off nt
	v_add_u32_e32 v0, 0x400, v4
	v_ashrrev_i32_e32 v16, 6, v0
	v_add_u32_e32 v0, s88, v16
	v_ashrrev_i32_e32 v1, 31, v0
	v_lshlrev_b64 v[0:1], 12, v[0:1]
	v_lshl_add_u64 v[0:1], s[4:5], 0, v[0:1]
	v_lshl_add_u64 v[0:1], v[0:1], 0, v[2:3]
	global_load_dword v17, v[0:1], off nt
	v_add_u32_e32 v0, 0x500, v4
	v_ashrrev_i32_e32 v18, 6, v0
	v_add_u32_e32 v0, s88, v18
	v_ashrrev_i32_e32 v1, 31, v0
	v_lshlrev_b64 v[0:1], 12, v[0:1]
	v_lshl_add_u64 v[0:1], s[4:5], 0, v[0:1]
	v_lshl_add_u64 v[0:1], v[0:1], 0, v[2:3]
	global_load_dword v19, v[0:1], off nt
	v_add_u32_e32 v0, 0x600, v4
	v_ashrrev_i32_e32 v20, 6, v0
	v_add_u32_e32 v0, s88, v20
	v_ashrrev_i32_e32 v1, 31, v0
	v_lshlrev_b64 v[0:1], 12, v[0:1]
	v_lshl_add_u64 v[0:1], s[4:5], 0, v[0:1]
	v_lshl_add_u64 v[0:1], v[0:1], 0, v[2:3]
	global_load_dword v21, v[0:1], off nt
	v_add_u32_e32 v0, 0x700, v4
	v_ashrrev_i32_e32 v22, 6, v0
	v_add_u32_e32 v0, s88, v22
	v_ashrrev_i32_e32 v1, 31, v0
	v_lshlrev_b64 v[0:1], 12, v[0:1]
	v_lshl_add_u64 v[0:1], s[4:5], 0, v[0:1]
	v_lshl_add_u64 v[0:1], v[0:1], 0, v[2:3]
	global_load_dword v23, v[0:1], off nt
	v_add_u32_e32 v0, 0x800, v4
	v_ashrrev_i32_e32 v24, 6, v0
	v_add_u32_e32 v0, s88, v24
	v_ashrrev_i32_e32 v1, 31, v0
	v_lshlrev_b64 v[0:1], 12, v[0:1]
	v_lshl_add_u64 v[0:1], s[4:5], 0, v[0:1]
	v_lshl_add_u64 v[0:1], v[0:1], 0, v[2:3]
	global_load_dword v25, v[0:1], off nt
	v_add_u32_e32 v0, 0x900, v4
	v_ashrrev_i32_e32 v26, 6, v0
	v_add_u32_e32 v0, s88, v26
	v_ashrrev_i32_e32 v1, 31, v0
	v_lshlrev_b64 v[0:1], 12, v[0:1]
	v_lshl_add_u64 v[0:1], s[4:5], 0, v[0:1]
	v_lshl_add_u64 v[0:1], v[0:1], 0, v[2:3]
	global_load_dword v27, v[0:1], off nt
	v_add_u32_e32 v0, 0xa00, v4
	v_ashrrev_i32_e32 v28, 6, v0
	v_add_u32_e32 v0, s88, v28
	v_ashrrev_i32_e32 v1, 31, v0
	v_lshlrev_b64 v[0:1], 12, v[0:1]
	v_lshl_add_u64 v[0:1], s[4:5], 0, v[0:1]
	v_lshl_add_u64 v[0:1], v[0:1], 0, v[2:3]
	global_load_dword v29, v[0:1], off nt
	v_add_u32_e32 v0, 0xb00, v4
	v_ashrrev_i32_e32 v30, 6, v0
	v_add_u32_e32 v0, s88, v30
	v_ashrrev_i32_e32 v1, 31, v0
	v_lshlrev_b64 v[0:1], 12, v[0:1]
	v_lshl_add_u64 v[0:1], s[4:5], 0, v[0:1]
	v_lshl_add_u64 v[0:1], v[0:1], 0, v[2:3]
	global_load_dword v31, v[0:1], off nt
	v_add_u32_e32 v0, 0xc00, v4
	v_ashrrev_i32_e32 v32, 6, v0
	v_add_u32_e32 v0, s88, v32
	v_ashrrev_i32_e32 v1, 31, v0
	v_lshlrev_b64 v[0:1], 12, v[0:1]
	v_lshl_add_u64 v[0:1], s[4:5], 0, v[0:1]
	v_lshl_add_u64 v[0:1], v[0:1], 0, v[2:3]
	global_load_dword v33, v[0:1], off nt
	v_add_u32_e32 v0, 0xd00, v4
	v_ashrrev_i32_e32 v34, 6, v0
	v_add_u32_e32 v0, s88, v34
	v_ashrrev_i32_e32 v1, 31, v0
	v_lshlrev_b64 v[0:1], 12, v[0:1]
	v_lshl_add_u64 v[0:1], s[4:5], 0, v[0:1]
	v_lshl_add_u64 v[0:1], v[0:1], 0, v[2:3]
	global_load_dword v35, v[0:1], off nt
	v_add_u32_e32 v0, 0xe00, v4
	v_ashrrev_i32_e32 v36, 6, v0
	v_add_u32_e32 v0, s88, v36
	v_ashrrev_i32_e32 v1, 31, v0
	v_lshlrev_b64 v[0:1], 12, v[0:1]
	v_lshl_add_u64 v[0:1], s[4:5], 0, v[0:1]
	v_lshl_add_u64 v[0:1], v[0:1], 0, v[2:3]
	global_load_dword v37, v[0:1], off nt
	v_add_u32_e32 v0, 0xf00, v4
	v_ashrrev_i32_e32 v38, 6, v0
	v_add_u32_e32 v0, s88, v38
	v_ashrrev_i32_e32 v1, 31, v0
	v_lshlrev_b64 v[0:1], 12, v[0:1]
	v_lshl_add_u64 v[0:1], s[4:5], 0, v[0:1]
	v_lshl_add_u64 v[0:1], v[0:1], 0, v[2:3]
	global_load_dword v2, v[0:1], off nt
	v_lshl_add_u32 v0, v8, 2, 0
	v_mad_u64_u32 v[6:7], s[26:27], v5, s71, v[0:1]
	s_waitcnt vmcnt(15)
	ds_write_b32 v6, v9
	v_mad_u64_u32 v[6:7], s[26:27], v10, s71, v[0:1]
	s_waitcnt vmcnt(14)
	ds_write_b32 v6, v11
	v_mad_u64_u32 v[6:7], s[26:27], v12, s71, v[0:1]
	s_waitcnt vmcnt(13)
	ds_write_b32 v6, v13
	v_mad_u64_u32 v[6:7], s[26:27], v14, s71, v[0:1]
	s_waitcnt vmcnt(12)
	ds_write_b32 v6, v15
	v_mad_u64_u32 v[6:7], s[26:27], v16, s71, v[0:1]
	s_waitcnt vmcnt(11)
	ds_write_b32 v6, v17
	v_mad_u64_u32 v[6:7], s[26:27], v18, s71, v[0:1]
	s_waitcnt vmcnt(10)
	ds_write_b32 v6, v19
	v_mad_u64_u32 v[6:7], s[26:27], v20, s71, v[0:1]
	s_waitcnt vmcnt(9)
	ds_write_b32 v6, v21
	v_mad_u64_u32 v[6:7], s[26:27], v22, s71, v[0:1]
	s_waitcnt vmcnt(8)
	ds_write_b32 v6, v23
	v_mad_u64_u32 v[6:7], s[26:27], v24, s71, v[0:1]
	s_waitcnt vmcnt(7)
	ds_write_b32 v6, v25
	v_mad_u64_u32 v[6:7], s[26:27], v26, s71, v[0:1]
	v_mad_u32_u24 v5, v8, s71, 0
	s_waitcnt vmcnt(6)
	ds_write_b32 v6, v27
	v_mad_u64_u32 v[6:7], s[26:27], v28, s71, v[0:1]
	s_waitcnt vmcnt(5)
	ds_write_b32 v6, v29
	v_mad_u64_u32 v[6:7], s[26:27], v30, s71, v[0:1]
	s_waitcnt vmcnt(4)
	ds_write_b32 v6, v31
	v_mad_u64_u32 v[6:7], s[26:27], v32, s71, v[0:1]
	s_waitcnt vmcnt(3)
	ds_write_b32 v6, v33
	v_mad_u64_u32 v[6:7], s[26:27], v34, s71, v[0:1]
	s_waitcnt vmcnt(2)
	ds_write_b32 v6, v35
	v_mad_u64_u32 v[6:7], s[26:27], v36, s71, v[0:1]
	v_mad_u64_u32 v[0:1], s[26:27], v38, s71, v[0:1]
	s_lshl_b64 s[26:27], s[88:89], 1
	s_add_u32 s26, s28, s26
	s_addc_u32 s27, s29, s27
	s_waitcnt vmcnt(1)
	ds_write_b32 v6, v37
	s_waitcnt vmcnt(0)
	ds_write_b32 v0, v2
	v_lshlrev_b32_e32 v2, 1, v8
	v_lshl_add_u64 v[0:1], s[26:27], 0, v[2:3]
	s_mov_b64 s[26:27], 0xf94c000
	v_lshl_add_u64 v[0:1], v[0:1], 0, s[26:27]
	s_waitcnt lgkmcnt(0)
	s_barrier

; __device__ __forceinline__ void ml_p3_item(const Params& p, int l, int item, unsigned* flag, char* ldsraw) {
;     ...
;     for (int j = eq; j < 64; j += 4) {
;       float sv = 0.f;
;       if (j <= t) {
;         float dot = 0.f;
; #pragma unroll
;         for (int d = 0; d < 32; d++) dot += qv[d] * Ks[j * 33 + d];
;         sv = dot * __expf(gt + Bs[j] - mt);
;       }
;       Ss[t * 65 + j] = sv;
;     }
.LBB0_374:
	v_cmp_le_i32_e32 vcc, v39, v232
	v_mov_b32_e32 v40, 0
	s_and_saveexec_b64 s[30:31], vcc
	s_cbranch_execz .LBB0_373
	ds_read2_b32 v[44:45], v37 offset1:1
	ds_read2_b32 v[46:47], v37 offset0:2 offset1:3
	ds_read2_b32 v[48:49], v37 offset0:4 offset1:5
	ds_read2_b32 v[50:51], v37 offset0:6 offset1:7
	ds_read2_b32 v[52:53], v37 offset0:8 offset1:9
	ds_read2_b32 v[54:55], v37 offset0:10 offset1:11
	ds_read2_b32 v[56:57], v37 offset0:12 offset1:13
	ds_read2_b32 v[58:59], v37 offset0:14 offset1:15
	ds_read2_b32 v[60:61], v37 offset0:16 offset1:17
	ds_read2_b32 v[62:63], v37 offset0:18 offset1:19
	ds_read2_b32 v[64:65], v37 offset0:20 offset1:21
	ds_read2_b32 v[66:67], v37 offset0:22 offset1:23
	ds_read2_b32 v[68:69], v37 offset0:24 offset1:25
	ds_read2_b32 v[70:71], v37 offset0:26 offset1:27
	s_waitcnt lgkmcnt(13)
	ds_read2_b32 v[72:73], v37 offset0:28 offset1:29
	v_fma_f32 v42, v4, v44, 0
	v_fmac_f32_e32 v42, v5, v45
	s_waitcnt lgkmcnt(13)
	ds_read2_b32 v[40:41], v37 offset0:30 offset1:31
	v_fmac_f32_e32 v42, v6, v46
	v_fmac_f32_e32 v42, v7, v47
	s_waitcnt lgkmcnt(13)
	ds_read_b32 v76, v36 offset:17024
	v_fmac_f32_e32 v42, v8, v48
	v_fmac_f32_e32 v42, v9, v49
	s_waitcnt lgkmcnt(13)
	v_fmac_f32_e32 v42, v10, v50
	v_fmac_f32_e32 v42, v11, v51
	s_waitcnt lgkmcnt(12)
	v_fmac_f32_e32 v42, v12, v52
	v_fmac_f32_e32 v42, v13, v53
	s_waitcnt lgkmcnt(11)
	v_fmac_f32_e32 v42, v14, v54
	v_fmac_f32_e32 v42, v15, v55
	s_waitcnt lgkmcnt(10)
	v_fmac_f32_e32 v42, v16, v56
	v_fmac_f32_e32 v42, v17, v57
	s_waitcnt lgkmcnt(9)
	v_fmac_f32_e32 v42, v18, v58
	v_fmac_f32_e32 v42, v19, v59
	s_waitcnt lgkmcnt(8)
	v_fmac_f32_e32 v42, v20, v60
	v_fmac_f32_e32 v42, v21, v61
	s_waitcnt lgkmcnt(7)
	v_fmac_f32_e32 v42, v22, v62
	v_fmac_f32_e32 v42, v23, v63
	s_waitcnt lgkmcnt(6)
	v_pk_mul_f32 v[64:65], v[24:25], v[64:65]
	s_nop 0
	v_add_f32_e32 v64, v42, v64
	v_add_f32_e32 v42, v64, v65
	s_waitcnt lgkmcnt(5)
	v_pk_mul_f32 v[66:67], v[26:27], v[66:67]
	s_nop 0
	v_add_f32_e32 v66, v42, v66
	v_add_f32_e32 v42, v66, v67
	s_waitcnt lgkmcnt(4)
	v_pk_mul_f32 v[68:69], v[28:29], v[68:69]
	s_nop 0
	v_add_f32_e32 v68, v42, v68
	v_add_f32_e32 v42, v68, v69
	s_waitcnt lgkmcnt(3)
	v_pk_mul_f32 v[70:71], v[30:31], v[70:71]
	s_nop 0
	v_add_f32_e32 v70, v42, v70
	v_add_f32_e32 v42, v70, v71
	s_waitcnt lgkmcnt(2)
	v_pk_mul_f32 v[72:73], v[32:33], v[72:73]
	s_nop 0
	v_add_f32_e32 v72, v42, v72
	v_add_f32_e32 v42, v72, v73
	s_waitcnt lgkmcnt(1)
	v_pk_mul_f32 v[40:41], v[34:35], v[40:41]
	s_nop 0
	v_add_f32_e32 v40, v42, v40
	v_add_f32_e32 v40, v40, v41
	s_waitcnt lgkmcnt(0)
	v_add_f32_e32 v41, v0, v76
	v_sub_f32_e32 v41, v41, v1
	v_mul_f32_e32 v41, 0x3fb8aa3b, v41
	v_exp_f32_e32 v41, v41
	s_nop 0
	v_mul_f32_e32 v40, v40, v41
	s_branch .LBB0_373

; __device__ __forceinline__ int opaque_tid() { int t = threadIdx.x; asm volatile("" : "+v"(t)); return t; }
; #define LDS3 __attribute__((address_space(3)))
; __device__ __forceinline__ void attn_item(const Params& p, int l, int bh, int qt, char* lds) {
;     ...
;   const int b = bh >> 2, h = bh & 3, q0 = qt * 128;
;   const int tid = opaque_tid(), lane = tid & 63, wid = tid >> 6, fr = lane & 15, fq = lane >> 4;
;   char* Ks = lds;
;   char* Vs = lds + 49152;
;   bf16x8 qf[2][6];
; #pragma unroll
;   for (int qs = 0; qs < 2; qs++)
; #pragma unroll
;     for (int kc = 0; kc < 6; kc++)
;       qf[qs][kc] = *(const bf16x8*)(Q + (bh * S + q0 + wid * 32 + qs * 16 + fr) * 192 + kc * 32 + fq * 8);
;   f32x4 o[2][8];
; #pragma unroll
;   for (int qs = 0; qs < 2; qs++)
; #pragma unroll
;     for (int nd = 0; nd < 8; nd++) o[qs][nd] = (f32x4){0.f, 0.f, 0.f, 0.f};
;   float mrow[2] = {-1e30f, -1e30f}, lrow[2] = {0.f, 0.f};
;   const int nkt = (q0 + 128) >> 6;
;     ...
;   auto dmaK = [&](int kt, int bi) {
;     int tt = tid; asm volatile("" : "+v"(tt));
;     char* kb = Ks + bi * 24576;
; #pragma unroll
;     for (int i = 0; i < 6; i++) {
;       const int g = i * 256 + tt; const int row = g / 24, cp = g - row * 24;
;       const int c = (cp & ~7) | ((cp & 7) ^ ((row >> 1) & 7));
;       const bf16_t* src_ = (c < 16) ? (KN + (bh * S + kt * 64 + row) * 128 + c * 8) : (KPE + (b * S + kt * 64 + row) * 64 + (c - 16) * 8);
;       __builtin_amdgcn_global_load_lds((const unsigned*)src_, (LDS3 unsigned*)(kb + i * 4096 + tt * 16), 16, 0, 0);
;     }
;   };
;   auto dmaV = [&](int kt) {
;     int tt = tid; asm volatile("" : "+v"(tt));
; #pragma unroll
;     for (int i = 0; i < 4; i++) {
;       const int g = i * 256 + tt; const int row = g >> 3, cp = g & 7; const int c = cp ^ ((row >> 1) & 7);
;       __builtin_amdgcn_global_load_lds((const unsigned*)(VT + (bh * 128 + row) * S + kt * 64 + c * 8), (LDS3 unsigned*)(Vs + i * 4096 + tt * 16), 16, 0, 0);
;     }
;   };
;   dmaK(0, 0); dmaV(0);
.LBB0_382:
	s_andn2_b64 vcc, exec, s[26:27]
	s_cbranch_vccnz .LBB0_451
	s_and_b32 s34, s78, 15
	s_mov_b32 s2, s89
	s_add_u32 s26, s46, s2
	s_addc_u32 s27, s47, 0
	s_mov_b32 s2, s89
	s_add_u32 s28, s46, s2
	s_addc_u32 s29, s47, 0
	s_mov_b32 s2, s89
	s_add_u32 s30, s46, s2
	s_addc_u32 s31, s47, 0
	s_lshl_b32 s2, s78, 3
	s_and_b32 s2, s2, 0x1f80
	s_mov_b32 s3, s89
	s_mov_b32 s43, s89
	s_sub_i32 s42, 0x1600, s2
	v_mov_b32_e32 v177, v198
	s_lshl_b32 s35, s34, 12
	s_add_i32 s35, s42, s35
	v_and_b32_e32 v175, 15, v177
	v_bfe_u32 v8, v177, 4, 2
	v_ashrrev_i32_e32 v0, 1, v177
	v_and_b32_e32 v176, 0xffffffe0, v0
	v_or_b32_e32 v0, s35, v175
	v_lshlrev_b32_e32 v2, 4, v8
	v_add_u32_e32 v4, v0, v176
	v_lshl_add_u64 v[0:1], s[26:27], 0, v[2:3]
	s_movk_i32 s26, 0xc0
	s_mov_b64 s[4:5], 0x4da8000
	v_mul_lo_u32 v4, v4, s26
	v_lshl_add_u64 v[0:1], v[0:1], 0, s[4:5]
	v_ashrrev_i32_e32 v5, 31, v4
	v_lshl_add_u64 v[6:7], v[4:5], 1, v[0:1]
	v_add_u32_e32 v4, 0xc00, v4
	v_ashrrev_i32_e32 v5, 31, v4
	v_lshl_add_u64 v[0:1], v[4:5], 1, v[0:1]
	global_load_dwordx4 v[36:39], v[6:7], off
	global_load_dwordx4 v[40:43], v[6:7], off offset:64
	global_load_dwordx4 v[44:47], v[6:7], off offset:128
	global_load_dwordx4 v[48:51], v[6:7], off offset:192
	global_load_dwordx4 v[52:55], v[6:7], off offset:256
	global_load_dwordx4 v[56:59], v[6:7], off offset:320
	global_load_dwordx4 v[60:63], v[0:1], off
	global_load_dwordx4 v[64:67], v[0:1], off offset:64
	global_load_dwordx4 v[68:71], v[0:1], off offset:128
	global_load_dwordx4 v[72:75], v[0:1], off offset:192
	global_load_dwordx4 v[76:79], v[0:1], off offset:256
	global_load_dwordx4 v[80:83], v[0:1], off offset:320
	v_mov_b32_e32 v0, v177
	s_add_u32 s26, s28, 0x65a8000
	v_mul_hi_i32 v1, v0, s73
	v_lshrrev_b32_e32 v2, 31, v1
	v_ashrrev_i32_e32 v1, 2, v1
	s_addc_u32 s27, s29, 0
	v_add_u32_e32 v1, v1, v2
	s_add_u32 s28, s30, 0x75a8000
	v_lshrrev_b32_e32 v2, 1, v1
	s_addc_u32 s29, s31, 0
	v_mad_u64_u32 v[4:5], s[30:31], v1, s74, v[0:1]
	v_xor_b32_e32 v2, v2, v0
	v_bfi_b32 v2, -8, v4, v2
	s_bfe_u32 s79, s78, 0x20002
	v_cmp_lt_i32_e32 vcc, 15, v2
	v_lshlrev_b32_e32 v4, 3, v2
	s_and_saveexec_b64 s[30:31], vcc
	s_xor_b64 s[30:31], exec, s[30:31]
	s_lshl_b32 s35, s79, 18
	v_lshl_add_u32 v6, v1, 6, s35
	v_ashrrev_i32_e32 v7, 31, v6
	v_lshl_add_u64 v[6:7], v[6:7], 1, s[28:29]
	v_add_u32_e32 v2, 0xffffff80, v4
	v_lshl_add_u64 v[6:7], v[2:3], 1, v[6:7]
	s_andn2_saveexec_b64 s[30:31], s[30:31]
	s_lshl_b32 s35, s34, 19
	v_lshl_add_u32 v6, v1, 7, s35
	v_ashrrev_i32_e32 v7, 31, v6
	v_lshl_add_u64 v[6:7], v[6:7], 1, s[26:27]
	v_ashrrev_i32_e32 v5, 31, v4
	v_lshl_add_u64 v[6:7], v[4:5], 1, v[6:7]
	s_or_b64 exec, exec, s[30:31]
	v_lshlrev_b32_e32 v1, 4, v0
	v_add_u32_e32 v9, 0, v1
	v_add_u32_e32 v2, 0x100, v0
	v_readfirstlane_b32 s30, v9
	s_mov_b32 m0, s30
	v_mul_hi_i32 v1, v2, s73
	global_load_lds_dwordx4 v[6:7], off
	v_lshrrev_b32_e32 v4, 31, v1
	v_ashrrev_i32_e32 v1, 2, v1
	v_add_u32_e32 v1, v1, v4
	v_mad_u64_u32 v[4:5], s[30:31], v1, s74, v[2:3]
	v_lshrrev_b32_e32 v2, 1, v1
	v_xor_b32_e32 v2, v2, v0
	v_bfi_b32 v2, -8, v4, v2
	v_cmp_lt_i32_e32 vcc, 15, v2
	v_lshlrev_b32_e32 v4, 3, v2
	s_and_saveexec_b64 s[30:31], vcc
	s_xor_b64 s[30:31], exec, s[30:31]
	s_lshl_b32 s35, s79, 18
	v_lshl_add_u32 v6, v1, 6, s35
	v_ashrrev_i32_e32 v7, 31, v6
	v_lshl_add_u64 v[6:7], v[6:7], 1, s[28:29]
	v_add_u32_e32 v2, 0xffffff80, v4
	v_lshl_add_u64 v[6:7], v[2:3], 1, v[6:7]
	s_andn2_saveexec_b64 s[30:31], s[30:31]
	s_lshl_b32 s35, s34, 19
	v_lshl_add_u32 v6, v1, 7, s35
	v_ashrrev_i32_e32 v7, 31, v6
	v_lshl_add_u64 v[6:7], v[6:7], 1, s[26:27]
	v_ashrrev_i32_e32 v5, 31, v4
	v_lshl_add_u64 v[6:7], v[4:5], 1, v[6:7]
	s_or_b64 exec, exec, s[30:31]
	v_add_u32_e32 v1, 0x1000, v9
	v_add_u32_e32 v2, 0x200, v0
	v_readfirstlane_b32 s30, v1
	s_mov_b32 m0, s30
	v_mul_hi_i32 v1, v2, s73
	global_load_lds_dwordx4 v[6:7], off
	v_lshrrev_b32_e32 v4, 31, v1
	v_ashrrev_i32_e32 v1, 2, v1
	v_add_u32_e32 v1, v1, v4
	v_mad_u64_u32 v[4:5], s[30:31], v1, s74, v[2:3]
	v_lshrrev_b32_e32 v2, 1, v1
	v_xor_b32_e32 v2, v2, v0
	v_bfi_b32 v2, -8, v4, v2
	v_cmp_lt_i32_e32 vcc, 15, v2
	v_lshlrev_b32_e32 v4, 3, v2
	s_and_saveexec_b64 s[30:31], vcc
	s_xor_b64 s[30:31], exec, s[30:31]
	s_lshl_b32 s35, s79, 18
	v_lshl_add_u32 v6, v1, 6, s35
	v_ashrrev_i32_e32 v7, 31, v6
	v_lshl_add_u64 v[6:7], v[6:7], 1, s[28:29]
	v_add_u32_e32 v2, 0xffffff80, v4
	v_lshl_add_u64 v[6:7], v[2:3], 1, v[6:7]
	s_andn2_saveexec_b64 s[30:31], s[30:31]
	s_lshl_b32 s35, s34, 19
	v_lshl_add_u32 v6, v1, 7, s35
	v_ashrrev_i32_e32 v7, 31, v6
	v_lshl_add_u64 v[6:7], v[6:7], 1, s[26:27]
	v_ashrrev_i32_e32 v5, 31, v4
	v_lshl_add_u64 v[6:7], v[4:5], 1, v[6:7]
	s_or_b64 exec, exec, s[30:31]
	v_add_u32_e32 v1, 0x2000, v9
	v_add_u32_e32 v2, 0x300, v0
	v_readfirstlane_b32 s30, v1
	s_mov_b32 m0, s30
	v_mul_hi_i32 v1, v2, s73
	global_load_lds_dwordx4 v[6:7], off
	v_lshrrev_b32_e32 v4, 31, v1
	v_ashrrev_i32_e32 v1, 2, v1
	v_add_u32_e32 v1, v1, v4
	v_mad_u64_u32 v[4:5], s[30:31], v1, s74, v[2:3]
	v_lshrrev_b32_e32 v2, 1, v1
	v_xor_b32_e32 v2, v2, v0
	v_bfi_b32 v2, -8, v4, v2
	v_cmp_lt_i32_e32 vcc, 15, v2
	v_lshlrev_b32_e32 v4, 3, v2
	s_and_saveexec_b64 s[30:31], vcc
	s_xor_b64 s[30:31], exec, s[30:31]
	s_lshl_b32 s35, s79, 18
	v_lshl_add_u32 v6, v1, 6, s35
	v_ashrrev_i32_e32 v7, 31, v6
	v_lshl_add_u64 v[6:7], v[6:7], 1, s[28:29]
	v_add_u32_e32 v2, 0xffffff80, v4
	v_lshl_add_u64 v[6:7], v[2:3], 1, v[6:7]
	s_andn2_saveexec_b64 s[30:31], s[30:31]
	s_lshl_b32 s35, s34, 19
	v_lshl_add_u32 v6, v1, 7, s35
	v_ashrrev_i32_e32 v7, 31, v6
	v_lshl_add_u64 v[6:7], v[6:7], 1, s[26:27]
	v_ashrrev_i32_e32 v5, 31, v4
	v_lshl_add_u64 v[6:7], v[4:5], 1, v[6:7]
; #define LDS3 __attribute__((address_space(3)))
; __device__ __forceinline__ void attn_item(const Params& p, int l, int bh, int qt, char* lds) {
;     ...
;   auto dmaK = [&](int kt, int bi) {
;     int tt = tid; asm volatile("" : "+v"(tt));
;     char* kb = Ks + bi * 24576;
; #pragma unroll
;     for (int i = 0; i < 6; i++) {
;       const int g = i * 256 + tt; const int row = g / 24, cp = g - row * 24;
;       const int c = (cp & ~7) | ((cp & 7) ^ ((row >> 1) & 7));
;       const bf16_t* src_ = (c < 16) ? (KN + (bh * S + kt * 64 + row) * 128 + c * 8) : (KPE + (b * S + kt * 64 + row) * 64 + (c - 16) * 8);
;       __builtin_amdgcn_global_load_lds((const unsigned*)src_, (LDS3 unsigned*)(kb + i * 4096 + tt * 16), 16, 0, 0);
;     }
;   };
;   auto dmaV = [&](int kt) {
;     int tt = tid; asm volatile("" : "+v"(tt));
; #pragma unroll
;     for (int i = 0; i < 4; i++) {
;       const int g = i * 256 + tt; const int row = g >> 3, cp = g & 7; const int c = cp ^ ((row >> 1) & 7);
;       __builtin_amdgcn_global_load_lds((const unsigned*)(VT + (bh * 128 + row) * S + kt * 64 + c * 8), (LDS3 unsigned*)(Vs + i * 4096 + tt * 16), 16, 0, 0);
;     }
;   };
;   dmaK(0, 0); dmaV(0);
;     ...
;           const int krow_ = ks * 16 + fr, kcl_ = kc * 4 + fq;
;           const bf16x8 kf = *(const bf16x8*)(kb + (krow_ * 24 + ((kcl_ & ~7) | ((kcl_ & 7) ^ ((krow_ >> 1) & 7)))) * 16);
	s_or_b64 exec, exec, s[30:31]
	v_add_u32_e32 v1, 0x3000, v9
	v_add_u32_e32 v2, 0x400, v0
	v_readfirstlane_b32 s30, v1
	s_mov_b32 m0, s30
	v_mul_hi_i32 v1, v2, s73
	global_load_lds_dwordx4 v[6:7], off
	v_lshrrev_b32_e32 v4, 31, v1
	v_ashrrev_i32_e32 v1, 2, v1
	v_add_u32_e32 v1, v1, v4
	v_mad_u64_u32 v[4:5], s[30:31], v1, s74, v[2:3]
	v_lshrrev_b32_e32 v2, 1, v1
	v_xor_b32_e32 v2, v2, v0
	v_bfi_b32 v2, -8, v4, v2
	v_cmp_lt_i32_e32 vcc, 15, v2
	v_lshlrev_b32_e32 v4, 3, v2
	s_and_saveexec_b64 s[30:31], vcc
	s_xor_b64 s[30:31], exec, s[30:31]
	s_lshl_b32 s35, s79, 18
	v_lshl_add_u32 v6, v1, 6, s35
	v_ashrrev_i32_e32 v7, 31, v6
	v_lshl_add_u64 v[6:7], v[6:7], 1, s[28:29]
	v_add_u32_e32 v2, 0xffffff80, v4
	v_lshl_add_u64 v[6:7], v[2:3], 1, v[6:7]
	s_andn2_saveexec_b64 s[30:31], s[30:31]
	s_lshl_b32 s35, s34, 19
	v_lshl_add_u32 v6, v1, 7, s35
	v_ashrrev_i32_e32 v7, 31, v6
	v_lshl_add_u64 v[6:7], v[6:7], 1, s[26:27]
	v_ashrrev_i32_e32 v5, 31, v4
	v_lshl_add_u64 v[6:7], v[4:5], 1, v[6:7]
	s_or_b64 exec, exec, s[30:31]
	v_add_u32_e32 v1, 0x4000, v9
	v_add_u32_e32 v4, 0x500, v0
	v_readfirstlane_b32 s30, v1
	s_mov_b32 m0, s30
	v_mul_hi_i32 v1, v4, s73
	global_load_lds_dwordx4 v[6:7], off
	v_lshrrev_b32_e32 v2, 31, v1
	v_ashrrev_i32_e32 v1, 2, v1
	v_add_u32_e32 v2, v1, v2
	v_lshrrev_b32_e32 v1, 1, v2
	v_mad_u64_u32 v[4:5], s[30:31], v2, s74, v[4:5]
	v_xor_b32_e32 v0, v1, v0
	v_bfi_b32 v0, -8, v4, v0
	v_cmp_lt_i32_e32 vcc, 15, v0
	v_lshlrev_b32_e32 v4, 3, v0
	s_and_saveexec_b64 s[30:31], vcc
	s_xor_b64 s[30:31], exec, s[30:31]
	s_lshl_b32 s35, s79, 18
	v_lshl_add_u32 v0, v2, 6, s35
	v_ashrrev_i32_e32 v1, 31, v0
	v_lshl_add_u64 v[0:1], v[0:1], 1, s[28:29]
	v_add_u32_e32 v2, 0xffffff80, v4
	v_lshl_add_u64 v[0:1], v[2:3], 1, v[0:1]
	s_lshl_b32 s36, s34, 19
	s_or_saveexec_b64 s[30:31], s[30:31]
	v_mov_b32_e32 v5, s35
	v_mov_b32_e32 v178, s36
	s_xor_b64 exec, exec, s[30:31]
	s_lshl_b32 s34, s34, 19
	v_lshl_add_u32 v0, v2, 7, s34
	v_ashrrev_i32_e32 v1, 31, v0
	v_mov_b32_e32 v178, s34
	v_lshl_add_u64 v[0:1], v[0:1], 1, s[26:27]
	v_ashrrev_i32_e32 v5, 31, v4
	s_lshl_b32 s34, s79, 18
	v_lshl_add_u64 v[0:1], v[4:5], 1, v[0:1]
	v_mov_b32_e32 v5, s34
	s_or_b64 exec, exec, s[30:31]
	s_add_u32 s3, s46, s3
	s_addc_u32 s31, s47, 0
	s_add_u32 s30, s3, 0x77a8000
	s_addc_u32 s31, s31, 0
	s_sub_i32 s2, 0x1680, s2
	v_add_u32_e32 v2, 0x5000, v9
	s_lshr_b32 s96, s2, 6
	v_readfirstlane_b32 s2, v2
	s_mov_b32 m0, s2
	v_mov_b32_e32 v4, v177
	global_load_lds_dwordx4 v[0:1], off
	v_lshlrev_b32_e32 v174, 2, v8
	v_lshrrev_b32_e32 v0, 4, v4
	v_xor_b32_e32 v2, v0, v4
	v_lshlrev_b32_e32 v0, 9, v4
	v_and_b32_e32 v0, 0xfffff000, v0
	v_add_u32_e32 v0, v0, v178
	v_ashrrev_i32_e32 v1, 31, v0
	v_lshl_add_u64 v[6:7], v[0:1], 1, s[30:31]
	v_lshlrev_b32_e32 v1, 4, v2
	v_lshl_add_u32 v4, v4, 4, 0
	v_and_b32_e32 v2, 0x70, v1
	v_add_u32_e32 v1, 0xc000, v4
	v_lshl_add_u64 v[6:7], v[6:7], 0, v[2:3]
	v_readfirstlane_b32 s2, v1
	s_mov_b32 m0, s2
	v_add_u32_e32 v1, 0xd000, v4
	global_load_lds_dwordx4 v[6:7], off
	v_add_u32_e32 v6, 0x20000, v0
	v_ashrrev_i32_e32 v7, 31, v6
	v_lshl_add_u64 v[6:7], v[6:7], 1, s[30:31]
	v_readfirstlane_b32 s2, v1
	v_lshl_add_u64 v[6:7], v[6:7], 0, v[2:3]
	s_mov_b32 m0, s2
	v_add_u32_e32 v1, 0xe000, v4
	global_load_lds_dwordx4 v[6:7], off
	v_add_u32_e32 v6, 0x40000, v0
	v_add_u32_e32 v0, 0x60000, v0
	v_ashrrev_i32_e32 v7, 31, v6
	v_readfirstlane_b32 s2, v1
	v_ashrrev_i32_e32 v1, 31, v0
	v_lshl_add_u64 v[6:7], v[6:7], 1, s[30:31]
	v_lshl_add_u64 v[0:1], v[0:1], 1, s[30:31]
	v_lshl_add_u64 v[6:7], v[6:7], 0, v[2:3]
	v_lshl_add_u64 v[0:1], v[0:1], 0, v[2:3]
	v_add_u32_e32 v2, 0xf000, v4
	s_mov_b32 m0, s2
	v_readfirstlane_b32 s2, v2
	global_load_lds_dwordx4 v[6:7], off
	s_mov_b32 m0, s2
	v_bfe_u32 v2, v177, 1, 3
	global_load_lds_dwordx4 v[0:1], off
	v_mul_u32_u24_e32 v4, 24, v175
	v_bitop3_b32 v6, v8, v4, v2 bitop3:0xde
	v_lshlrev_b32_e32 v184, 4, v6
	v_or_b32_e32 v6, 4, v8
	v_bitop3_b32 v4, v6, v4, v2 bitop3:0xde
	v_lshlrev_b32_e32 v185, 4, v4
	v_mad_u32_u24 v4, v175, 24, 8
	v_bitop3_b32 v9, v4, v8, v2 bitop3:0xf6
	v_bitop3_b32 v4, v6, v4, v2 bitop3:0xde
	v_lshlrev_b32_e32 v187, 4, v4
	v_mad_u32_u24 v4, v175, 24, 16
	v_lshlrev_b32_e32 v186, 4, v9
	v_bitop3_b32 v9, v4, v8, v2 bitop3:0xf6
	v_bitop3_b32 v4, v6, v4, v2 bitop3:0xde
	v_lshlrev_b32_e32 v189, 4, v4
	v_mov_b32_e32 v4, 0x180
	v_mad_u32_u24 v4, v175, 24, v4
	v_lshlrev_b32_e32 v188, 4, v9
	v_bitop3_b32 v9, v4, v8, v2 bitop3:0xf6
	v_bitop3_b32 v4, v6, v4, v2 bitop3:0xde
	v_lshlrev_b32_e32 v191, 4, v4
	v_mov_b32_e32 v4, 0x188
	v_mad_u32_u24 v4, v175, 24, v4
	v_lshlrev_b32_e32 v190, 4, v9
	v_bitop3_b32 v9, v4, v8, v2 bitop3:0xf6
	v_bitop3_b32 v4, v6, v4, v2 bitop3:0xde
	v_lshlrev_b32_e32 v193, 4, v4
	v_mov_b32_e32 v4, 0x190
	v_mad_u32_u24 v4, v175, 24, v4
	v_lshlrev_b32_e32 v192, 4, v9
	v_bitop3_b32 v9, v4, v8, v2 bitop3:0xf6
	v_bitop3_b32 v4, v6, v4, v2 bitop3:0xde
	v_lshlrev_b32_e32 v195, 4, v4
	v_mov_b32_e32 v4, 0x300
	v_mad_u32_u24 v4, v175, 24, v4
	v_lshlrev_b32_e32 v194, 4, v9
	v_bitop3_b32 v9, v4, v8, v2 bitop3:0xf6
	v_bitop3_b32 v4, v6, v4, v2 bitop3:0xde
	v_lshlrev_b32_e32 v197, 4, v4
	v_mov_b32_e32 v4, 0x308
	v_mad_u32_u24 v4, v175, 24, v4
	v_lshlrev_b32_e32 v196, 4, v9
	v_bitop3_b32 v9, v4, v8, v2 bitop3:0xf6
	v_bitop3_b32 v4, v6, v4, v2 bitop3:0xde
	v_lshlrev_b32_e32 v233, 4, v4
	v_mov_b32_e32 v4, 0x310
	v_mad_u32_u24 v4, v175, 24, v4
	v_lshlrev_b32_e32 v232, 4, v9
	v_bitop3_b32 v9, v4, v8, v2 bitop3:0xf6
	v_bitop3_b32 v4, v6, v4, v2 bitop3:0xde
	v_lshlrev_b32_e32 v235, 4, v4
	v_mad_u32_u24 v4, v175, 24, v227
	v_lshlrev_b32_e32 v234, 4, v9
	v_bitop3_b32 v9, v4, v8, v2 bitop3:0xf6
	v_bitop3_b32 v4, v6, v4, v2 bitop3:0xde
; #define LDS3 __attribute__((address_space(3)))
; __device__ __forceinline__ void attn_item(const Params& p, int l, int bh, int qt, char* lds) {
;     ...
;   f32x4 o[2][8];
; #pragma unroll
;   for (int qs = 0; qs < 2; qs++)
; #pragma unroll
;     for (int nd = 0; nd < 8; nd++) o[qs][nd] = (f32x4){0.f, 0.f, 0.f, 0.f};
;   float mrow[2] = {-1e30f, -1e30f}, lrow[2] = {0.f, 0.f};
;   const int nkt = (q0 + 128) >> 6;
;     ...
;   auto dmaK = [&](int kt, int bi) {
;     int tt = tid; asm volatile("" : "+v"(tt));
;     char* kb = Ks + bi * 24576;
; #pragma unroll
;     for (int i = 0; i < 6; i++) {
;       const int g = i * 256 + tt; const int row = g / 24, cp = g - row * 24;
;       const int c = (cp & ~7) | ((cp & 7) ^ ((row >> 1) & 7));
;       const bf16_t* src_ = (c < 16) ? (KN + (bh * S + kt * 64 + row) * 128 + c * 8) : (KPE + (b * S + kt * 64 + row) * 64 + (c - 16) * 8);
;       __builtin_amdgcn_global_load_lds((const unsigned*)src_, (LDS3 unsigned*)(kb + i * 4096 + tt * 16), 16, 0, 0);
;     }
;   };
;   auto dmaV = [&](int kt) {
;     int tt = tid; asm volatile("" : "+v"(tt));
; #pragma unroll
;     for (int i = 0; i < 4; i++) {
;       const int g = i * 256 + tt; const int row = g >> 3, cp = g & 7; const int c = cp ^ ((row >> 1) & 7);
;       __builtin_amdgcn_global_load_lds((const unsigned*)(VT + (bh * 128 + row) * S + kt * 64 + c * 8), (LDS3 unsigned*)(Vs + i * 4096 + tt * 16), 16, 0, 0);
;     }
;   };
;   dmaK(0, 0); dmaV(0);
;   asm volatile("s_waitcnt vmcnt(0)" ::: "memory"); __builtin_amdgcn_s_barrier(); asm volatile("" ::: "memory");
;     ...
;           const int vrow_ = nd * 16 + fr;
;           const bf16x8 vf = *(const bf16x8*)(Vs + (vrow_ * 8 + ((c2 * 4 + fq) ^ ((vrow_ >> 1) & 7))) * 16);
	v_lshlrev_b32_e32 v237, 4, v4
	v_mov_b32_e32 v4, 0x488
	v_mad_u32_u24 v4, v175, 24, v4
	v_lshlrev_b32_e32 v236, 4, v9
	v_bitop3_b32 v9, v4, v8, v2 bitop3:0xf6
	v_bitop3_b32 v4, v6, v4, v2 bitop3:0xde
	v_add_u32_e32 v0, s42, v176
	v_lshlrev_b32_e32 v239, 4, v4
	v_mad_u32_u24 v4, v175, 24, v230
	v_or_b32_e32 v179, 31, v0
	v_or_b32_e32 v180, v0, v175
	v_lshlrev_b32_e32 v0, 3, v175
	v_lshlrev_b32_e32 v238, 4, v9
	v_bitop3_b32 v9, v4, v8, v2 bitop3:0xf6
	v_bitop3_b32 v4, v6, v4, v2 bitop3:0xde
	v_lshrrev_b32_e32 v1, 1, v177
	v_bitop3_b32 v7, v8, v2, 4 bitop3:0x36
	v_lshlrev_b32_e32 v241, 4, v4
	v_bitop3_b32 v4, v8, v0, v2 bitop3:0xde
	v_bitop3_b32 v2, v6, v0, v2 bitop3:0xde
	v_bitop3_b32 v1, v8, v1, 7 bitop3:0x78
	v_lshlrev_b32_e32 v240, 4, v9
	v_lshlrev_b32_e32 v9, 4, v2
	v_or_b32_e32 v2, 0x80, v0
	v_lshlrev_b32_e32 v8, 4, v4
	v_or_b32_e32 v4, v1, v2
	v_or_b32_e32 v2, v7, v2
	v_lshlrev_b32_e32 v11, 4, v2
	v_or_b32_e32 v2, 0x100, v0
	v_lshlrev_b32_e32 v10, 4, v4
	v_or_b32_e32 v4, v1, v2
	v_or_b32_e32 v2, v7, v2
	v_lshlrev_b32_e32 v13, 4, v2
	v_or_b32_e32 v2, 0x180, v0
	v_lshlrev_b32_e32 v12, 4, v4
	v_or_b32_e32 v4, v1, v2
	v_or_b32_e32 v2, v7, v2
	v_lshlrev_b32_e32 v15, 4, v2
	v_or_b32_e32 v2, 0x200, v0
	v_lshlrev_b32_e32 v14, 4, v4
	v_or_b32_e32 v4, v1, v2
	v_or_b32_e32 v2, v7, v2
	v_lshlrev_b32_e32 v17, 4, v2
	v_or_b32_e32 v2, 0x280, v0
	v_lshlrev_b32_e32 v16, 4, v4
	v_or_b32_e32 v4, v1, v2
	v_or_b32_e32 v2, v7, v2
	s_waitcnt vmcnt(0)
	v_lshlrev_b32_e32 v19, 4, v2
	v_or_b32_e32 v2, 0x300, v0
	v_lshlrev_b32_e32 v18, 4, v4
	v_or_b32_e32 v4, v1, v2
	v_or_b32_e32 v2, v7, v2
	v_or_b32_e32 v0, 0x380, v0
	s_waitcnt vmcnt(0)
	s_barrier
	v_lshlrev_b32_e32 v20, 4, v4
	v_lshlrev_b32_e32 v21, 4, v2
	v_or_b32_e32 v1, v1, v0
	v_or_b32_e32 v0, v7, v0
	v_mov_b32_e32 v6, v3
	v_mov_b32_e32 v7, v3
	v_lshlrev_b32_e32 v1, 4, v1
	v_lshlrev_b32_e32 v0, 4, v0
	v_add_u32_e32 v244, 0x1000, v5
	v_mov_b32_e32 v2, v3
	v_mov_b32_e32 v4, v3
	v_mov_b32_e32 v5, v3
	v_add_u32_e32 v245, 0, v8
	v_add_u32_e32 v246, 0, v9
	v_add_u32_e32 v247, 0, v10
	v_add_u32_e32 v248, 0, v11
	v_add_u32_e32 v249, 0, v12
	v_add_u32_e32 v250, 0, v13
	v_add_u32_e32 v251, 0, v14
	v_add_u32_e32 v203, 0, v15
	v_add_u32_e32 v219, 0, v16
	v_add_u32_e32 v220, 0, v17
	v_add_u32_e32 v221, 0, v18
	v_add_u32_e32 v222, 0, v19
	v_add_u32_e32 v223, 0, v20
	v_add_u32_e32 v224, 0, v21
	v_mov_b64_e32 v[10:11], v[6:7]
	v_mov_b64_e32 v[14:15], v[6:7]
	v_mov_b64_e32 v[18:19], v[6:7]
	v_mov_b64_e32 v[22:23], v[6:7]
	v_mov_b64_e32 v[26:27], v[6:7]
	v_mov_b64_e32 v[30:31], v[6:7]
	v_mov_b64_e32 v[34:35], v[6:7]
	v_mov_b64_e32 v[86:87], v[6:7]
	v_mov_b64_e32 v[90:91], v[6:7]
	v_mov_b64_e32 v[94:95], v[6:7]
	v_mov_b64_e32 v[98:99], v[6:7]
	v_mov_b64_e32 v[102:103], v[6:7]
	v_mov_b64_e32 v[106:107], v[6:7]
	v_mov_b64_e32 v[110:111], v[6:7]
	v_mov_b64_e32 v[114:115], v[6:7]
	s_add_i32 s97, s96, -2
	v_or_b32_e32 v181, 0x20000, v178
	v_or_b32_e32 v182, 0x40000, v178
	v_or_b32_e32 v183, 0x60000, v178
	v_or_b32_e32 v242, 16, v180
	v_add_u32_e32 v243, 0x2000, v178
	v_mov_b32_e32 v166, 0xf149f2ca
	s_mov_b32 s66, 0
	v_add_u32_e32 v225, 0, v1
	v_add_u32_e32 v226, 0, v0
	v_mov_b64_e32 v[8:9], v[4:5]
	v_mov_b64_e32 v[12:13], v[4:5]
	v_mov_b64_e32 v[16:17], v[4:5]
	v_mov_b64_e32 v[20:21], v[4:5]
	v_mov_b64_e32 v[24:25], v[4:5]
	v_mov_b64_e32 v[28:29], v[4:5]
	v_mov_b64_e32 v[32:33], v[4:5]
	v_mov_b64_e32 v[84:85], v[4:5]
	v_mov_b64_e32 v[88:89], v[4:5]
	v_mov_b64_e32 v[92:93], v[4:5]
	v_mov_b64_e32 v[96:97], v[4:5]
	v_mov_b64_e32 v[100:101], v[4:5]
	v_mov_b64_e32 v[104:105], v[4:5]
	v_mov_b64_e32 v[108:109], v[4:5]
	v_mov_b64_e32 v[112:113], v[4:5]
	v_mov_b32_e32 v164, 0xf149f2ca
	s_mov_b32 s2, 0
	v_mov_b64_e32 v[0:1], v[2:3]
	v_lshlrev_b32_e32 v139, 5, v177
	v_add_u32_e32 v139, 0x10000, v139
	v_mov_b32_e32 v151, 0
	v_mov_b32_e32 v132, v177
	s_nop 0
	v_mul_hi_i32 v150, v132, s73
	v_lshrrev_b32_e32 v133, 31, v150
	v_ashrrev_i32_e32 v150, 2, v150
	v_add_u32_e32 v150, v150, v133
	v_mad_u64_u32 v[134:135], s[34:35], v150, s74, v[132:133]
	v_lshrrev_b32_e32 v133, 1, v150
	v_xor_b32_e32 v133, v133, v132
	v_bfi_b32 v133, -8, v134, v133
	v_cmp_lt_i32_e32 vcc, 15, v133
	v_lshlrev_b32_e32 v134, 3, v133
	s_and_saveexec_b64 s[34:35], vcc
	s_xor_b64 s[34:35], exec, s[34:35]
	v_lshl_add_u32 v136, v150, 6, v244
	v_ashrrev_i32_e32 v137, 31, v136
	v_lshl_add_u64 v[136:137], v[136:137], 1, s[28:29]
	v_add_u32_e32 v150, 0xffffff80, v134
	v_lshl_add_u64 v[136:137], v[150:151], 1, v[136:137]
	s_andn2_saveexec_b64 s[34:35], s[34:35]
	v_lshl_add_u32 v136, v150, 7, v243
	v_ashrrev_i32_e32 v137, 31, v136
	v_lshl_add_u64 v[136:137], v[136:137], 1, s[26:27]
	v_ashrrev_i32_e32 v135, 31, v134
	v_lshl_add_u64 v[136:137], v[134:135], 1, v[136:137]
	v_or_b32_e32 v136, 1, v136
	s_or_b64 exec, exec, s[34:35]
	s_bitcmp1_b32 s67, 0
	s_cselect_b32 s3, 0x6000, 0
	s_add_i32 s3, s3, 0
	v_lshlrev_b32_e32 v150, 4, v132
	v_add_u32_e32 v138, s3, v150
	v_add_u32_e32 v134, 0x100, v132
	v_readfirstlane_b32 s3, v138
	v_mul_hi_i32 v150, v134, s73
	v_subrev_u32_e32 v136, s46, v136
	ds_write_b32 v139, v136 offset:0
	v_lshrrev_b32_e32 v133, 31, v150
	v_ashrrev_i32_e32 v150, 2, v150
	v_add_u32_e32 v150, v150, v133
	v_lshrrev_b32_e32 v133, 1, v150
	v_mad_u64_u32 v[134:135], s[34:35], v150, s74, v[134:135]
	v_xor_b32_e32 v133, v133, v132
	v_bfi_b32 v133, -8, v134, v133
	v_cmp_lt_i32_e32 vcc, 15, v133
	v_lshlrev_b32_e32 v134, 3, v133
	s_and_saveexec_b64 s[34:35], vcc
	s_xor_b64 s[34:35], exec, s[34:35]
	v_lshl_add_u32 v136, v150, 6, v244
; #define LDS3 __attribute__((address_space(3)))
; __device__ __forceinline__ void attn_item(const Params& p, int l, int bh, int qt, char* lds) {
;     ...
;   auto dmaK = [&](int kt, int bi) {
;     int tt = tid; asm volatile("" : "+v"(tt));
;     char* kb = Ks + bi * 24576;
; #pragma unroll
;     for (int i = 0; i < 6; i++) {
;       const int g = i * 256 + tt; const int row = g / 24, cp = g - row * 24;
;       const int c = (cp & ~7) | ((cp & 7) ^ ((row >> 1) & 7));
;       const bf16_t* src_ = (c < 16) ? (KN + (bh * S + kt * 64 + row) * 128 + c * 8) : (KPE + (b * S + kt * 64 + row) * 64 + (c - 16) * 8);
;       __builtin_amdgcn_global_load_lds((const unsigned*)src_, (LDS3 unsigned*)(kb + i * 4096 + tt * 16), 16, 0, 0);
;     }
;   };
;   auto dmaV = [&](int kt) {
;     int tt = tid; asm volatile("" : "+v"(tt));
; #pragma unroll
;     for (int i = 0; i < 4; i++) {
;       const int g = i * 256 + tt; const int row = g >> 3, cp = g & 7; const int c = cp ^ ((row >> 1) & 7);
;       __builtin_amdgcn_global_load_lds((const unsigned*)(VT + (bh * 128 + row) * S + kt * 64 + c * 8), (LDS3 unsigned*)(Vs + i * 4096 + tt * 16), 16, 0, 0);
;     }
;   };
	v_ashrrev_i32_e32 v137, 31, v136
	v_lshl_add_u64 v[136:137], v[136:137], 1, s[28:29]
	v_add_u32_e32 v150, 0xffffff80, v134
	v_lshl_add_u64 v[136:137], v[150:151], 1, v[136:137]
	s_andn2_saveexec_b64 s[34:35], s[34:35]
	v_lshl_add_u32 v136, v150, 7, v243
	v_ashrrev_i32_e32 v137, 31, v136
	v_lshl_add_u64 v[136:137], v[136:137], 1, s[26:27]
	v_ashrrev_i32_e32 v135, 31, v134
	v_lshl_add_u64 v[136:137], v[134:135], 1, v[136:137]
	v_or_b32_e32 v136, 1, v136
	s_or_b64 exec, exec, s[34:35]
	v_add_u32_e32 v150, 0x1000, v138
	v_add_u32_e32 v134, 0x200, v132
	v_readfirstlane_b32 s3, v150
	v_mul_hi_i32 v150, v134, s73
	v_subrev_u32_e32 v136, s46, v136
	ds_write_b32 v139, v136 offset:4
	v_lshrrev_b32_e32 v133, 31, v150
	v_ashrrev_i32_e32 v150, 2, v150
	v_add_u32_e32 v150, v150, v133
	v_lshrrev_b32_e32 v133, 1, v150
	v_mad_u64_u32 v[134:135], s[34:35], v150, s74, v[134:135]
	v_xor_b32_e32 v133, v133, v132
	v_bfi_b32 v133, -8, v134, v133
	v_cmp_lt_i32_e32 vcc, 15, v133
	v_lshlrev_b32_e32 v134, 3, v133
	s_and_saveexec_b64 s[34:35], vcc
	s_xor_b64 s[34:35], exec, s[34:35]
	v_lshl_add_u32 v136, v150, 6, v244
	v_ashrrev_i32_e32 v137, 31, v136
	v_lshl_add_u64 v[136:137], v[136:137], 1, s[28:29]
	v_add_u32_e32 v150, 0xffffff80, v134
	v_lshl_add_u64 v[136:137], v[150:151], 1, v[136:137]
	s_andn2_saveexec_b64 s[34:35], s[34:35]
	v_lshl_add_u32 v136, v150, 7, v243
	v_ashrrev_i32_e32 v137, 31, v136
	v_lshl_add_u64 v[136:137], v[136:137], 1, s[26:27]
	v_ashrrev_i32_e32 v135, 31, v134
	v_lshl_add_u64 v[136:137], v[134:135], 1, v[136:137]
	v_or_b32_e32 v136, 1, v136
	s_or_b64 exec, exec, s[34:35]
	v_add_u32_e32 v150, 0x2000, v138
	v_add_u32_e32 v134, 0x300, v132
	v_readfirstlane_b32 s3, v150
	v_mul_hi_i32 v150, v134, s73
	v_subrev_u32_e32 v136, s46, v136
	ds_write_b32 v139, v136 offset:8
	v_lshrrev_b32_e32 v133, 31, v150
	v_ashrrev_i32_e32 v150, 2, v150
	v_add_u32_e32 v150, v150, v133
	v_lshrrev_b32_e32 v133, 1, v150
	v_mad_u64_u32 v[134:135], s[34:35], v150, s74, v[134:135]
	v_xor_b32_e32 v133, v133, v132
	v_bfi_b32 v133, -8, v134, v133
	v_cmp_lt_i32_e32 vcc, 15, v133
	v_lshlrev_b32_e32 v134, 3, v133
	s_and_saveexec_b64 s[34:35], vcc
	s_xor_b64 s[34:35], exec, s[34:35]
	v_lshl_add_u32 v136, v150, 6, v244
	v_ashrrev_i32_e32 v137, 31, v136
	v_lshl_add_u64 v[136:137], v[136:137], 1, s[28:29]
	v_add_u32_e32 v150, 0xffffff80, v134
	v_lshl_add_u64 v[136:137], v[150:151], 1, v[136:137]
	s_andn2_saveexec_b64 s[34:35], s[34:35]
	v_lshl_add_u32 v136, v150, 7, v243
	v_ashrrev_i32_e32 v137, 31, v136
	v_lshl_add_u64 v[136:137], v[136:137], 1, s[26:27]
	v_ashrrev_i32_e32 v135, 31, v134
	v_lshl_add_u64 v[136:137], v[134:135], 1, v[136:137]
	v_or_b32_e32 v136, 1, v136
	s_or_b64 exec, exec, s[34:35]
	v_add_u32_e32 v150, 0x3000, v138
	v_add_u32_e32 v134, 0x400, v132
	v_readfirstlane_b32 s3, v150
	v_mul_hi_i32 v150, v134, s73
	v_subrev_u32_e32 v136, s46, v136
	ds_write_b32 v139, v136 offset:12
	v_lshrrev_b32_e32 v133, 31, v150
	v_ashrrev_i32_e32 v150, 2, v150
	v_add_u32_e32 v150, v150, v133
	v_lshrrev_b32_e32 v133, 1, v150
	v_mad_u64_u32 v[134:135], s[34:35], v150, s74, v[134:135]
	v_xor_b32_e32 v133, v133, v132
	v_bfi_b32 v133, -8, v134, v133
	v_cmp_lt_i32_e32 vcc, 15, v133
	v_lshlrev_b32_e32 v134, 3, v133
	s_and_saveexec_b64 s[34:35], vcc
	s_xor_b64 s[34:35], exec, s[34:35]
	v_lshl_add_u32 v136, v150, 6, v244
	v_ashrrev_i32_e32 v137, 31, v136
	v_lshl_add_u64 v[136:137], v[136:137], 1, s[28:29]
	v_add_u32_e32 v150, 0xffffff80, v134
	v_lshl_add_u64 v[136:137], v[150:151], 1, v[136:137]
	s_andn2_saveexec_b64 s[34:35], s[34:35]
	v_lshl_add_u32 v136, v150, 7, v243
	v_ashrrev_i32_e32 v137, 31, v136
	v_lshl_add_u64 v[136:137], v[136:137], 1, s[26:27]
	v_ashrrev_i32_e32 v135, 31, v134
	v_lshl_add_u64 v[136:137], v[134:135], 1, v[136:137]
	v_or_b32_e32 v136, 1, v136
	s_or_b64 exec, exec, s[34:35]
	v_add_u32_e32 v150, 0x4000, v138
	v_add_u32_e32 v134, 0x500, v132
	v_readfirstlane_b32 s3, v150
	v_mul_hi_i32 v150, v134, s73
	v_subrev_u32_e32 v136, s46, v136
	ds_write_b32 v139, v136 offset:16
	v_lshrrev_b32_e32 v133, 31, v150
	v_ashrrev_i32_e32 v150, 2, v150
	v_add_u32_e32 v150, v150, v133
	v_lshrrev_b32_e32 v133, 1, v150
	v_mad_u64_u32 v[134:135], s[34:35], v150, s74, v[134:135]
	v_xor_b32_e32 v132, v133, v132
	v_bfi_b32 v132, -8, v134, v132
	v_cmp_lt_i32_e32 vcc, 15, v132
	v_lshlrev_b32_e32 v132, 3, v132
	s_and_saveexec_b64 s[34:35], vcc
	s_xor_b64 s[34:35], exec, s[34:35]
	v_lshl_add_u32 v134, v150, 6, v244
	v_ashrrev_i32_e32 v135, 31, v134
	v_lshl_add_u64 v[134:135], v[134:135], 1, s[28:29]
	v_add_u32_e32 v150, 0xffffff80, v132
	v_lshl_add_u64 v[134:135], v[150:151], 1, v[134:135]
	s_andn2_saveexec_b64 s[34:35], s[34:35]
	v_lshl_add_u32 v134, v150, 7, v243
	v_ashrrev_i32_e32 v135, 31, v134
	v_lshl_add_u64 v[134:135], v[134:135], 1, s[26:27]
	v_ashrrev_i32_e32 v133, 31, v132
	v_lshl_add_u64 v[134:135], v[132:133], 1, v[134:135]
	v_or_b32_e32 v134, 1, v134
	s_or_b64 exec, exec, s[34:35]
	v_add_u32_e32 v150, 0x5000, v138
	s_nop 0
	v_readfirstlane_b32 s3, v150
	s_nop 0
	v_subrev_u32_e32 v134, s46, v134
	ds_write_b32 v139, v134 offset:20
	v_lshlrev_b32_e32 v152, 9, v177
	v_and_b32_e32 v152, 0xfffff000, v152
	v_add_u32_e32 v152, v152, v178
	v_lshlrev_b32_e32 v152, 1, v152
	v_lshrrev_b32_e32 v153, 4, v177
	v_xor_b32_e32 v153, v153, v177
	v_lshlrev_b32_e32 v153, 4, v153
	v_and_b32_e32 v153, 0x70, v153
	v_add_u32_e32 v152, v152, v153
	s_sub_u32 s3, s30, s46
	v_add_u32_e32 v152, s3, v152
	ds_write_b32 v139, v152 offset:24
	s_waitcnt lgkmcnt(0)

; #define LDS3 __attribute__((address_space(3)))
; __device__ __forceinline__ void attn_item(const Params& p, int l, int bh, int qt, char* lds) {
;     ...
;   auto dmaK = [&](int kt, int bi) {
;     int tt = tid; asm volatile("" : "+v"(tt));
;     char* kb = Ks + bi * 24576;
; #pragma unroll
;     for (int i = 0; i < 6; i++) {
;       const int g = i * 256 + tt; const int row = g / 24, cp = g - row * 24;
;       const int c = (cp & ~7) | ((cp & 7) ^ ((row >> 1) & 7));
;       const bf16_t* src_ = (c < 16) ? (KN + (bh * S + kt * 64 + row) * 128 + c * 8) : (KPE + (b * S + kt * 64 + row) * 64 + (c - 16) * 8);
;       __builtin_amdgcn_global_load_lds((const unsigned*)src_, (LDS3 unsigned*)(kb + i * 4096 + tt * 16), 16, 0, 0);
;     }
;   };
;     ...
;   for (int kt = 0; kt < nkt; kt++) {
;     const bool more = (kt + 1 < nkt);
;     const int k0 = kt * 64;
;     const bool active = (k0 <= q0 + wid * 32 + 31);
;     const char* kb = Ks + (kt & 1) * 24576;
;     if (more) dmaK(kt + 1, (kt + 1) & 1);
.LBB0_418:
	v_lshlrev_b32_e32 v138, 5, v177
	v_add_u32_e32 v138, 0x10000, v138
	ds_read_b128 v[132:135], v138 offset:0
	ds_read_b64 v[136:137], v138 offset:16
	s_add_i32 s3, s67, -1
	s_lshl_b32 vcc_hi, s3, 13
	s_add_u32 s34, s46, vcc_hi
	s_addc_u32 s35, s47, 0
	s_add_i32 vcc_lo, vcc_hi, -1
	v_lshlrev_b32_e32 v150, 4, v177
	s_bitcmp1_b32 s67, 0
	s_cselect_b32 s3, 0x6000, 0
	s_nop 0
	v_readfirstlane_b32 vcc_hi, v150
	s_nop 0
	s_add_i32 s3, s3, vcc_hi
	s_mov_b32 m0, s3
	s_waitcnt lgkmcnt(1)
	v_bfe_i32 v151, v132, 0, 1
	v_and_b32_e32 v151, vcc_lo, v151
	v_add_u32_e32 v151, v132, v151
	global_load_lds_dwordx4 v151, s[34:35]
	s_add_i32 s3, s3, 0x1000
	s_mov_b32 m0, s3
	v_bfe_i32 v152, v133, 0, 1
	v_and_b32_e32 v152, vcc_lo, v152
	v_add_u32_e32 v152, v133, v152
	global_load_lds_dwordx4 v152, s[34:35]
	s_add_i32 s3, s3, 0x1000
	s_mov_b32 m0, s3
	v_bfe_i32 v151, v134, 0, 1
	v_and_b32_e32 v151, vcc_lo, v151
	v_add_u32_e32 v151, v134, v151
	global_load_lds_dwordx4 v151, s[34:35]
	s_add_i32 s3, s3, 0x1000
	s_mov_b32 m0, s3
	v_bfe_i32 v152, v135, 0, 1
	v_and_b32_e32 v152, vcc_lo, v152
	v_add_u32_e32 v152, v135, v152
	global_load_lds_dwordx4 v152, s[34:35]
	s_add_i32 s3, s3, 0x1000
	s_mov_b32 m0, s3
	s_waitcnt lgkmcnt(0)
	v_bfe_i32 v151, v136, 0, 1
	v_and_b32_e32 v151, vcc_lo, v151
	v_add_u32_e32 v151, v136, v151
	global_load_lds_dwordx4 v151, s[34:35]
	s_add_i32 s3, s3, 0x1000
	s_mov_b32 m0, s3
	v_bfe_i32 v152, v137, 0, 1
	v_and_b32_e32 v152, vcc_lo, v152
	v_add_u32_e32 v152, v137, v152
	global_load_lds_dwordx4 v152, s[34:35]
	v_cmp_le_i32_e64 s[34:35], s66, v179
	s_and_saveexec_b64 s[40:41], s[34:35]
	s_cbranch_execz .LBB0_410

; #define LDS3 __attribute__((address_space(3)))
; __device__ __forceinline__ void attn_item(const Params& p, int l, int bh, int qt, char* lds) {
;     ...
;   auto dmaV = [&](int kt) {
;     int tt = tid; asm volatile("" : "+v"(tt));
; #pragma unroll
;     for (int i = 0; i < 4; i++) {
;       const int g = i * 256 + tt; const int row = g >> 3, cp = g & 7; const int c = cp ^ ((row >> 1) & 7);
;       __builtin_amdgcn_global_load_lds((const unsigned*)(VT + (bh * 128 + row) * S + kt * 64 + c * 8), (LDS3 unsigned*)(Vs + i * 4096 + tt * 16), 16, 0, 0);
;     }
;   };
;     ...
;     asm volatile("s_waitcnt vmcnt(0) lgkmcnt(0)" ::: "memory"); __builtin_amdgcn_s_barrier(); asm volatile("" ::: "memory");
;     if (more) dmaV(kt + 1);
;   }
.LBB0_448:
	s_add_i32 s88, s66, 64
	v_lshlrev_b32_e32 v133, 5, v177
	v_add_u32_e32 v133, 0x10000, v133
	ds_read_b32 v132, v133 offset:24
	v_lshlrev_b32_e32 v134, 4, v177
	s_lshl_b32 s2, s88, 1
	s_add_u32 s2, s46, s2
	s_addc_u32 s3, s47, 0
	v_readfirstlane_b32 s34, v134
	s_nop 0
	s_add_i32 s34, s34, 0xc000
	s_mov_b32 m0, s34
	s_waitcnt lgkmcnt(0)
	global_load_lds_dwordx4 v132, s[2:3]
	s_add_u32 s2, s2, 0x40000
	s_addc_u32 s3, s3, 0
	s_add_i32 s34, s34, 0x1000
	s_mov_b32 m0, s34
	s_nop 0
	global_load_lds_dwordx4 v132, s[2:3]
	s_add_u32 s2, s2, 0x40000
	s_addc_u32 s3, s3, 0
	s_add_i32 s34, s34, 0x1000
	s_mov_b32 m0, s34
	s_nop 0
	global_load_lds_dwordx4 v132, s[2:3]
	s_add_u32 s2, s2, 0x40000
	s_addc_u32 s3, s3, 0
	s_add_i32 s34, s34, 0x1000
	s_mov_b32 m0, s34
	s_nop 0
	global_load_lds_dwordx4 v132, s[2:3]
	v_add_u32_e32 v243, 0x2000, v243
	s_cmp_lg_u32 s96, s67
	v_add_u32_e32 v244, 0x1000, v244
	s_cbranch_scc0 .LBB0_450
